# attention unit prologue: K/V tile 1 loads issued together with tile 0 (one load latency less per unit)
# speedup vs baseline: 1.0024x; 1.0024x over previous
.LBB0_218:
	s_bfe_u32 s4, s36, 0x30004
	v_lshl_add_u32 v0, s4, 9, v222
	v_ashrrev_i32_e32 v1, 31, v0
	v_lshl_add_u64 v[0:1], v[0:1], 2, s[14:15]
	global_load_dword v232, v[0:1], off
	s_lshl_b32 s5, s36, 6
	s_and_b32 s66, s5, 0x2000
	s_lshl_b32 s5, s21, 7
	s_add_i32 s5, s5, s58
	s_ashr_i32 s8, s5, 31
	s_add_u32 s62, s5, s66
	s_addc_u32 s63, s8, 0
	v_mov_b32_e32 v1, s63
	s_lshl_b32 s89, s4, 7
	s_lshl_b32 s4, s4, 8
	s_mov_b32 s5, s67
	s_mov_b32 s65, s67
	v_lshl_add_u64 v[2:3], s[66:67], 0, v[146:147]
	v_lshlrev_b64 v[2:3], 10, v[2:3]
	v_mov_b32_e32 v5, v3
	v_add_u32_e32 v20, 0, v159
	s_cmp_eq_u32 s21, 0


	v_or_b32_e32 v0, s62, v144
	v_lshlrev_b64 v[0:1], 11, v[0:1]
	v_lshl_add_u64 v[0:1], s[46:47], 0, v[0:1]
	v_lshl_add_u64 v[0:1], v[0:1], 0, s[4:5]
	v_lshl_add_u64 v[0:1], v[0:1], 0, s[64:65]
	v_lshl_add_u64 v[0:1], v[0:1], 0, v[208:209]
	global_load_dwordx4 v[112:115], v[0:1], off
	global_load_dwordx4 v[116:119], v[0:1], off offset:32
	global_load_dwordx4 v[120:123], v[0:1], off offset:64
	global_load_dwordx4 v[124:127], v[0:1], off offset:96
	v_or_b32_e32 v0, s89, v148
	v_or_b32_e32 v4, v2, v0
	v_lshlrev_b64 v[12:13], 1, v[4:5]
	v_lshl_add_u64 v[4:5], s[10:11], 0, v[12:13]
	global_load_dwordx4 v[4:7], v[4:5], off
	v_lshl_add_u64 v[8:9], s[12:13], 0, v[12:13]
	v_add_u32_e32 v1, 0, v157
	global_load_dwordx4 v[8:11], v[8:9], off
	s_mov_b64 s[4:5], 0x10000
	v_lshl_add_u64 v[16:17], v[12:13], 0, s[4:5]
	v_lshl_add_u64 v[12:13], s[10:11], 0, v[16:17]
	global_load_dwordx4 v[12:15], v[12:13], off
	v_lshl_add_u64 v[16:17], s[12:13], 0, v[16:17]
	global_load_dwordx4 v[16:19], v[16:17], off
	v_lshl_add_u64 v[24:25], s[66:67], 0, v[150:151]
	v_lshlrev_b64 v[24:25], 11, v[24:25]
	v_lshl_or_b32 v24, v0, 1, v24
	v_lshl_add_u64 v[26:27], s[10:11], 0, v[24:25]
	global_load_dwordx4 v[128:131], v[26:27], off
	v_lshl_add_u64 v[26:27], s[12:13], 0, v[24:25]
	v_lshl_add_u64 v[24:25], v[24:25], 0, s[4:5]
	global_load_dwordx4 v[132:135], v[26:27], off
	v_lshl_add_u64 v[26:27], s[10:11], 0, v[24:25]
	v_lshl_add_u64 v[24:25], s[12:13], 0, v[24:25]
	global_load_dwordx4 v[136:139], v[26:27], off
	global_load_dwordx4 v[140:143], v[24:25], off
	s_waitcnt vmcnt(7)
	ds_write_b32 v149, v232
	ds_write_b128 v1, v[4:7]
	s_waitcnt vmcnt(6)
	ds_write_b128 v20, v[8:11] offset:34816
	v_add_u32_e32 v8, 0, v161
	v_add_u32_e32 v9, 0, v163
	s_waitcnt vmcnt(5)
	ds_write_b128 v8, v[12:15]
	s_waitcnt vmcnt(4)
	ds_write_b128 v9, v[16:19] offset:34816
	s_waitcnt lgkmcnt(0)
	s_barrier
	s_waitcnt vmcnt(3)
	ds_write_b128 v1, v[128:131] offset:17408
	s_waitcnt vmcnt(2)
	ds_write_b128 v20, v[132:135] offset:55296
	s_waitcnt vmcnt(1)
	ds_write_b128 v8, v[136:139] offset:17408
	s_waitcnt vmcnt(0)
	ds_write_b128 v9, v[140:143] offset:55296
	s_cbranch_scc1 .LBB0_220
	v_mov_b32_e32 v1, v209
	v_lshl_add_u64 v[2:3], v[2:3], 0, s[78:79]
	v_or_b32_e32 v4, v2, v0
	v_mov_b32_e32 v5, v3
	v_lshl_add_u64 v[0:1], v[2:3], 0, v[0:1]
	v_lshlrev_b64 v[4:5], 1, v[4:5]
	v_lshl_add_u64 v[0:1], v[0:1], 1, v[214:215]
	v_lshl_add_u64 v[6:7], s[10:11], 0, v[4:5]
	v_lshl_add_u64 v[2:3], s[10:11], 0, v[0:1]
	v_lshl_add_u64 v[4:5], s[12:13], 0, v[4:5]
	global_load_dwordx4 v[128:131], v[6:7], off
	global_load_dwordx4 v[132:135], v[4:5], off
	v_lshl_add_u64 v[0:1], s[12:13], 0, v[0:1]
	global_load_dwordx4 v[136:139], v[2:3], off
	global_load_dwordx4 v[140:143], v[0:1], off
